# filter-generation k-loop: H2F row loads via SGPR base + 32-bit VGPR offset (15 VALU address ops per iteration replaced by scalar adds)
# baseline (speedup 1.0000x reference)
.LBB0_159:
	s_cmpk_gt_i32 s60, 0x1ff
	s_waitcnt lgkmcnt(0)
	s_barrier
	s_cbranch_scc1 .LBB0_226
	v_lshlrev_b32_e32 v182, 4, v144
	s_waitcnt vmcnt(0)
	v_mbcnt_lo_u32_b32 v0, -1, 0
	v_mbcnt_hi_u32_b32 v0, -1, v0
	v_and_b32_e32 v2, 64, v0
	v_add_u32_e32 v2, 64, v2
	v_xor_b32_e32 v3, 32, v0
	v_cmp_lt_i32_e32 vcc, v3, v2
	v_lshlrev_b32_e32 v1, 2, v144
	s_add_i32 s61, 0, 0x10800
	v_cndmask_b32_e32 v3, v0, v3, vcc
	v_lshlrev_b32_e32 v56, 2, v3
	v_xor_b32_e32 v3, 16, v0
	v_cmp_lt_i32_e32 vcc, v3, v2
	s_add_i32 s2, 0, 0x10900
	s_add_u32 s79, s22, 0x1aa00000
	v_cndmask_b32_e32 v3, v0, v3, vcc
	v_lshlrev_b32_e32 v57, 2, v3
	v_xor_b32_e32 v3, 8, v0
	v_cmp_lt_i32_e32 vcc, v3, v2
	s_addc_u32 s68, s23, 0
	s_add_i32 s33, 0, 0x10000
	v_cndmask_b32_e32 v3, v0, v3, vcc
	v_lshlrev_b32_e32 v58, 2, v3
	v_xor_b32_e32 v3, 4, v0
	v_cmp_lt_i32_e32 vcc, v3, v2
	v_add_u32_e32 v63, s61, v1
	v_add_u32_e32 v64, s2, v1
	v_cndmask_b32_e32 v3, v0, v3, vcc
	v_lshlrev_b32_e32 v59, 2, v3
	v_xor_b32_e32 v3, 2, v0
	v_cmp_lt_i32_e32 vcc, v3, v2
	v_add_u32_e32 v65, s33, v1
	s_mov_b64 s[8:9], s[94:95]
	v_cndmask_b32_e32 v3, v0, v3, vcc
	v_lshlrev_b32_e32 v60, 2, v3
	v_xor_b32_e32 v3, 1, v0
	v_cmp_lt_i32_e32 vcc, v3, v2
	v_cvt_f32_u32_e32 v2, v1
	v_readlane_b32 s80, v248, 8
	v_cndmask_b32_e32 v0, v0, v3, vcc
	v_or_b32_e32 v3, 1, v1
	v_cvt_f32_u32_e32 v4, v3
	v_mul_f32_e32 v66, 0xba000000, v2
	v_or_b32_e32 v2, 2, v1
	v_or_b32_e32 v1, 3, v1
	v_mul_f32_e32 v67, 0xba000000, v4
	v_cvt_f32_u32_e32 v4, v2
	v_cvt_f32_u32_e32 v6, v1
	v_mov_b32_e32 v33, 0
	v_readlane_b32 s92, v248, 20
	v_mul_f32_e32 v68, 0xba000000, v4
	v_lshlrev_b32_e32 v4, 5, v2
	v_lshlrev_b32_e32 v2, 11, v144
	v_mul_f32_e32 v69, 0xba000000, v6
	v_and_b32_e32 v32, 0xfc000, v2
	v_readlane_b32 s93, v248, 21
	v_lshlrev_b32_e32 v6, 10, v144
	v_lshlrev_b32_e32 v7, 5, v3
	v_lshl_add_u64 v[2:3], s[92:93], 0, v[32:33]
	v_and_b32_e32 v32, 0x1000, v6
	v_lshl_add_u64 v[34:35], v[2:3], 0, v[32:33]
	v_lshrrev_b32_e32 v2, 9, v144
	v_sub_u32_e32 v2, 0, v2
	v_lshlrev_b32_e32 v32, 4, v144
	v_and_b32_e32 v70, 3, v2
	v_lshl_add_u64 v[2:3], s[22:23], 0, v[32:33]
	s_mov_b64 s[10:11], 0x1bdda000
	v_lshlrev_b32_e32 v32, 1, v144
	v_lshl_add_u64 v[36:37], v[2:3], 0, s[10:11]
	v_lshl_add_u64 v[2:3], s[22:23], 0, v[32:33]
	s_mov_b64 s[10:11], 0x1aa01000
	v_lshl_add_u64 v[38:39], v[2:3], 0, s[10:11]
	s_lshl_b32 s2, s3, 2
	s_lshl_b32 s10, s78, 2
	s_movk_i32 s59, 0x200
	v_lshlrev_b32_e32 v61, 2, v0
	v_and_b32_e32 v0, 3, v144
	v_lshlrev_b32_e32 v5, 7, v144
	v_lshlrev_b32_e32 v1, 5, v1
	v_readlane_b32 s81, v248, 9
	v_readlane_b32 s84, v248, 12
	v_readlane_b32 s85, v248, 13
	v_readlane_b32 s86, v248, 14
	v_readlane_b32 s87, v248, 15
	v_readlane_b32 s88, v248, 16
	v_readlane_b32 s94, v248, 22
	v_readlane_b32 s95, v248, 23
	s_sub_i32 s80, s2, s10
	s_lshl_b32 s2, s26, 2
	v_cmp_gt_u32_e64 s[0:1], s59, v144
	s_mov_b32 s67, 0
	v_cmp_eq_u32_e64 s[6:7], 0, v85
	v_lshlrev_b32_e32 v62, 5, v125
	s_mov_b64 s[94:95], s[8:9]
	v_cmp_ne_u32_e64 s[8:9], 0, v70
	v_mov_b32_e32 v145, v33
	v_sub_u32_e32 v71, 0x800, v144
	s_sub_i32 s81, s2, s10
	v_lshl_add_u32 v72, v144, 5, 0
	v_lshlrev_b32_e32 v40, 2, v0
	v_mov_b32_e32 v73, 0x1000
	s_mov_b32 s84, 0x3fb8aa3b
	s_mov_b32 s85, 0xc2ce8ed0
	s_mov_b32 s86, 0x42b17218
	v_add_u32_e32 v74, 0, v5
	v_add_u32_e32 v75, 0, v7
	v_add_u32_e32 v76, 0, v4
	v_add_u32_e32 v77, 0, v1
	s_movk_i32 s87, 0x1fff
	s_movk_i32 s88, 0x400
	v_mov_b32_e32 v78, 0x7f800000
	v_mov_b32_e32 v79, 0x7ff
	v_readlane_b32 s82, v248, 10
	v_readlane_b32 s83, v248, 11
	v_readlane_b32 s89, v248, 17
	v_readlane_b32 s90, v248, 18
	v_readlane_b32 s91, v248, 19
	s_branch .LBB0_162

.LBB0_164:
	s_or_b64 exec, exec, s[12:13]
	s_or_b32 s10, s10, s14
	s_ashr_i32 s11, s10, 31
	s_lshl_b64 s[10:11], s[10:11], 2
	s_add_u32 s10, s36, s10
	s_addc_u32 s11, s37, s11
	s_waitcnt lgkmcnt(0)
	s_barrier
	global_load_dwordx4 v[4:7], v33, s[10:11]
	global_load_dwordx4 v[0:3], v73, s[10:11]
	v_mov_b32_e32 v52, 0
	s_mov_b32 s10, -8
	s_add_u32 s98, s22, 0x1bdcc000
	s_addc_u32 s99, s23, 0
	s_mov_b32 s11, s33
	v_mov_b32_e32 v53, v52
	v_mov_b32_e32 v50, v52
	v_mov_b32_e32 v51, v52
	v_mov_b32_e32 v12, v52
	v_mov_b32_e32 v13, v52
	v_mov_b32_e32 v14, v52
	v_mov_b32_e32 v15, v52
	v_mov_b32_e32 v16, v52
	v_mov_b32_e32 v17, v52
	v_mov_b32_e32 v18, v52
	v_mov_b32_e32 v19, v52
	v_mov_b32_e32 v20, v52
	v_mov_b32_e32 v21, v52
	v_mov_b32_e32 v22, v52
	v_mov_b32_e32 v23, v52
	v_mov_b32_e32 v24, v52
	v_mov_b32_e32 v25, v52
	v_mov_b32_e32 v26, v52
	v_mov_b32_e32 v27, v52
	v_mov_b32_e32 v28, v52
	v_mov_b32_e32 v29, v52
	v_mov_b32_e32 v30, v52
	v_mov_b32_e32 v31, v52
	v_mov_b32_e32 v48, v52
	v_mov_b32_e32 v49, v52
	v_mov_b32_e32 v46, v52
	v_mov_b32_e32 v47, v52
	v_mov_b32_e32 v44, v52
	v_mov_b32_e32 v45, v52
	v_mov_b32_e32 v42, v52
	v_mov_b32_e32 v43, v52
.LBB0_165:
	global_load_dwordx4 v[8:11], v182, s[98:99]
	s_add_u32 s98, s98, 0x2000
	s_addc_u32 s99, s99, 0
	global_load_dwordx4 v[80:83], v182, s[98:99]
	s_add_u32 s98, s98, 0x2000
	s_addc_u32 s99, s99, 0
	global_load_dwordx4 v[86:89], v182, s[98:99]
	s_add_u32 s98, s98, 0x2000
	s_addc_u32 s99, s99, 0
	global_load_dwordx4 v[90:93], v182, s[98:99]
	s_add_u32 s98, s98, 0x2000
	s_addc_u32 s99, s99, 0
	global_load_dwordx4 v[94:97], v182, s[98:99]
	s_add_u32 s98, s98, 0x2000
	s_addc_u32 s99, s99, 0
	global_load_dwordx4 v[98:101], v182, s[98:99]
	s_add_u32 s98, s98, 0x2000
	s_addc_u32 s99, s99, 0
	global_load_dwordx4 v[102:105], v182, s[98:99]
	s_add_u32 s98, s98, 0x2000
	s_addc_u32 s99, s99, 0
	global_load_dwordx4 v[106:109], v182, s[98:99]
	s_add_u32 s98, s98, 0x2000
	s_addc_u32 s99, s99, 0
	v_mov_b32_e32 v32, s11
	ds_read_b128 v[110:113], v32
	ds_read_b128 v[114:117], v32 offset:16
	ds_read_b128 v[118:121], v32 offset:32
	ds_read_b128 v[126:129], v32 offset:48
	ds_read_b128 v[130:133], v32 offset:64
	ds_read_b128 v[134:137], v32 offset:80
	ds_read_b128 v[138:141], v32 offset:96
	ds_read_b128 v[146:149], v32 offset:112
	ds_read_b128 v[150:153], v32 offset:128
	ds_read_b128 v[154:157], v32 offset:144
	ds_read_b128 v[158:161], v32 offset:160
	ds_read_b128 v[162:165], v32 offset:176
	ds_read_b128 v[166:169], v32 offset:192
	ds_read_b128 v[170:173], v32 offset:208
	ds_read_b128 v[174:177], v32 offset:224
	ds_read_b128 v[178:181], v32 offset:240
	s_add_i32 s10, s10, 8
	s_addk_i32 s11, 0x100
	s_cmp_lt_u32 s10, 56
	s_waitcnt vmcnt(7) lgkmcnt(14)
	v_pk_fma_f32 v[52:53], v[8:9], v[110:111], v[52:53] op_sel_hi:[0,1,1]
	v_pk_fma_f32 v[50:51], v[8:9], v[112:113], v[50:51] op_sel_hi:[0,1,1]
	v_pk_fma_f32 v[12:13], v[8:9], v[114:115], v[12:13] op_sel_hi:[0,1,1]
	v_pk_fma_f32 v[14:15], v[8:9], v[116:117], v[14:15] op_sel_hi:[0,1,1]
	v_pk_fma_f32 v[16:17], v[8:9], v[110:111], v[16:17] op_sel:[1,0,0]
	v_pk_fma_f32 v[18:19], v[8:9], v[112:113], v[18:19] op_sel:[1,0,0]
	v_pk_fma_f32 v[20:21], v[8:9], v[114:115], v[20:21] op_sel:[1,0,0]
	v_pk_fma_f32 v[8:9], v[8:9], v[116:117], v[22:23] op_sel:[1,0,0]
	s_waitcnt vmcnt(6)
	v_mov_b32_e32 v32, v83
	s_waitcnt lgkmcnt(12)
	v_pk_fma_f32 v[8:9], v[80:81], v[128:129], v[8:9] op_sel:[1,0,0]
	v_pk_fma_f32 v[52:53], v[80:81], v[118:119], v[52:53] op_sel_hi:[0,1,1]
	s_waitcnt vmcnt(5) lgkmcnt(10)
	v_pk_fma_f32 v[8:9], v[86:87], v[136:137], v[8:9] op_sel:[1,0,0]
	v_pk_fma_f32 v[50:51], v[80:81], v[120:121], v[50:51] op_sel_hi:[0,1,1]
	s_waitcnt vmcnt(4) lgkmcnt(8)
	v_pk_fma_f32 v[8:9], v[90:91], v[148:149], v[8:9] op_sel:[1,0,0]
	v_pk_fma_f32 v[12:13], v[80:81], v[126:127], v[12:13] op_sel_hi:[0,1,1]
	s_waitcnt vmcnt(3) lgkmcnt(6)
	v_pk_fma_f32 v[8:9], v[94:95], v[156:157], v[8:9] op_sel:[1,0,0]
	v_pk_fma_f32 v[14:15], v[80:81], v[128:129], v[14:15] op_sel_hi:[0,1,1]
	v_pk_fma_f32 v[16:17], v[80:81], v[118:119], v[16:17] op_sel:[1,0,0]
	s_waitcnt vmcnt(2) lgkmcnt(4)
	v_pk_fma_f32 v[8:9], v[98:99], v[164:165], v[8:9] op_sel:[1,0,0]
	v_pk_fma_f32 v[18:19], v[80:81], v[120:121], v[18:19] op_sel:[1,0,0]
	v_pk_fma_f32 v[20:21], v[80:81], v[126:127], v[20:21] op_sel:[1,0,0]
	v_mov_b32_e32 v80, v89
	v_mov_b32_e32 v84, v97
	s_waitcnt vmcnt(1) lgkmcnt(2)
	v_pk_fma_f32 v[8:9], v[102:103], v[172:173], v[8:9] op_sel:[1,0,0]
	v_pk_fma_f32 v[52:53], v[86:87], v[130:131], v[52:53] op_sel_hi:[0,1,1]
	s_waitcnt vmcnt(0) lgkmcnt(0)
	v_pk_fma_f32 v[22:23], v[106:107], v[180:181], v[8:9] op_sel:[1,0,0]
	v_pk_fma_f32 v[8:9], v[10:11], v[110:111], v[24:25] op_sel_hi:[0,1,1]
	v_pk_fma_f32 v[8:9], v[82:83], v[118:119], v[8:9] op_sel_hi:[0,1,1]
	v_pk_fma_f32 v[8:9], v[88:89], v[130:131], v[8:9] op_sel_hi:[0,1,1]
	v_pk_fma_f32 v[8:9], v[92:93], v[138:139], v[8:9] op_sel_hi:[0,1,1]
	v_pk_fma_f32 v[8:9], v[96:97], v[150:151], v[8:9] op_sel_hi:[0,1,1]
	v_pk_fma_f32 v[8:9], v[100:101], v[158:159], v[8:9] op_sel_hi:[0,1,1]
	v_pk_fma_f32 v[8:9], v[104:105], v[166:167], v[8:9] op_sel_hi:[0,1,1]
	v_pk_fma_f32 v[24:25], v[108:109], v[174:175], v[8:9] op_sel_hi:[0,1,1]
	v_pk_fma_f32 v[8:9], v[10:11], v[112:113], v[26:27] op_sel_hi:[0,1,1]
	v_pk_fma_f32 v[8:9], v[82:83], v[120:121], v[8:9] op_sel_hi:[0,1,1]
	v_pk_fma_f32 v[8:9], v[88:89], v[132:133], v[8:9] op_sel_hi:[0,1,1]
	v_pk_fma_f32 v[8:9], v[92:93], v[140:141], v[8:9] op_sel_hi:[0,1,1]
	v_pk_fma_f32 v[8:9], v[96:97], v[152:153], v[8:9] op_sel_hi:[0,1,1]
	v_pk_fma_f32 v[8:9], v[100:101], v[160:161], v[8:9] op_sel_hi:[0,1,1]
	v_pk_fma_f32 v[8:9], v[104:105], v[168:169], v[8:9] op_sel_hi:[0,1,1]
	v_pk_fma_f32 v[26:27], v[108:109], v[176:177], v[8:9] op_sel_hi:[0,1,1]
	v_pk_fma_f32 v[8:9], v[10:11], v[114:115], v[28:29] op_sel_hi:[0,1,1]
	v_pk_fma_f32 v[8:9], v[82:83], v[126:127], v[8:9] op_sel_hi:[0,1,1]
	v_pk_fma_f32 v[8:9], v[88:89], v[134:135], v[8:9] op_sel_hi:[0,1,1]
	v_pk_fma_f32 v[8:9], v[92:93], v[146:147], v[8:9] op_sel_hi:[0,1,1]
	v_pk_fma_f32 v[8:9], v[96:97], v[154:155], v[8:9] op_sel_hi:[0,1,1]
	v_pk_fma_f32 v[8:9], v[100:101], v[162:163], v[8:9] op_sel_hi:[0,1,1]
	v_pk_fma_f32 v[8:9], v[104:105], v[170:171], v[8:9] op_sel_hi:[0,1,1]
	v_pk_fma_f32 v[28:29], v[108:109], v[178:179], v[8:9] op_sel_hi:[0,1,1]
	v_pk_fma_f32 v[8:9], v[10:11], v[116:117], v[30:31] op_sel_hi:[0,1,1]
	v_pk_fma_f32 v[8:9], v[82:83], v[128:129], v[8:9] op_sel_hi:[0,1,1]
	v_pk_fma_f32 v[8:9], v[88:89], v[136:137], v[8:9] op_sel_hi:[0,1,1]
	v_pk_fma_f32 v[8:9], v[92:93], v[148:149], v[8:9] op_sel_hi:[0,1,1]
	v_pk_fma_f32 v[8:9], v[96:97], v[156:157], v[8:9] op_sel_hi:[0,1,1]
	v_pk_fma_f32 v[8:9], v[100:101], v[164:165], v[8:9] op_sel_hi:[0,1,1]
	v_pk_fma_f32 v[8:9], v[104:105], v[172:173], v[8:9] op_sel_hi:[0,1,1]
	v_pk_fma_f32 v[30:31], v[108:109], v[180:181], v[8:9] op_sel_hi:[0,1,1]
	v_mov_b32_e32 v8, v11
	v_pk_fma_f32 v[10:11], v[8:9], v[110:111], v[48:49] op_sel_hi:[0,1,1]
	v_pk_fma_f32 v[10:11], v[32:33], v[118:119], v[10:11] op_sel_hi:[0,1,1]
	v_pk_fma_f32 v[10:11], v[80:81], v[130:131], v[10:11] op_sel_hi:[0,1,1]
	v_mov_b32_e32 v82, v93
	v_pk_fma_f32 v[10:11], v[82:83], v[138:139], v[10:11] op_sel_hi:[0,1,1]
	v_pk_fma_f32 v[50:51], v[86:87], v[132:133], v[50:51] op_sel_hi:[0,1,1]
	v_pk_fma_f32 v[12:13], v[86:87], v[134:135], v[12:13] op_sel_hi:[0,1,1]
	v_pk_fma_f32 v[14:15], v[86:87], v[136:137], v[14:15] op_sel_hi:[0,1,1]
	v_pk_fma_f32 v[16:17], v[86:87], v[130:131], v[16:17] op_sel:[1,0,0]
	v_pk_fma_f32 v[18:19], v[86:87], v[132:133], v[18:19] op_sel:[1,0,0]
	v_pk_fma_f32 v[20:21], v[86:87], v[134:135], v[20:21] op_sel:[1,0,0]
	v_pk_fma_f32 v[10:11], v[84:85], v[150:151], v[10:11] op_sel_hi:[0,1,1]
	v_mov_b32_e32 v86, v101
	v_pk_fma_f32 v[10:11], v[86:87], v[158:159], v[10:11] op_sel_hi:[0,1,1]
	v_mov_b32_e32 v88, v105
	v_pk_fma_f32 v[52:53], v[90:91], v[138:139], v[52:53] op_sel_hi:[0,1,1]
	v_pk_fma_f32 v[50:51], v[90:91], v[140:141], v[50:51] op_sel_hi:[0,1,1]
	v_pk_fma_f32 v[12:13], v[90:91], v[146:147], v[12:13] op_sel_hi:[0,1,1]
	v_pk_fma_f32 v[14:15], v[90:91], v[148:149], v[14:15] op_sel_hi:[0,1,1]
	v_pk_fma_f32 v[16:17], v[90:91], v[138:139], v[16:17] op_sel:[1,0,0]
	v_pk_fma_f32 v[18:19], v[90:91], v[140:141], v[18:19] op_sel:[1,0,0]
	v_pk_fma_f32 v[20:21], v[90:91], v[146:147], v[20:21] op_sel:[1,0,0]
	v_pk_fma_f32 v[10:11], v[88:89], v[166:167], v[10:11] op_sel_hi:[0,1,1]
	v_mov_b32_e32 v90, v109
	v_pk_fma_f32 v[48:49], v[90:91], v[174:175], v[10:11] op_sel_hi:[0,1,1]
	v_pk_fma_f32 v[10:11], v[8:9], v[112:113], v[46:47] op_sel_hi:[0,1,1]
	v_pk_fma_f32 v[10:11], v[32:33], v[120:121], v[10:11] op_sel_hi:[0,1,1]
	v_pk_fma_f32 v[10:11], v[80:81], v[132:133], v[10:11] op_sel_hi:[0,1,1]
	v_pk_fma_f32 v[10:11], v[82:83], v[140:141], v[10:11] op_sel_hi:[0,1,1]
	v_pk_fma_f32 v[10:11], v[84:85], v[152:153], v[10:11] op_sel_hi:[0,1,1]
	v_pk_fma_f32 v[10:11], v[86:87], v[160:161], v[10:11] op_sel_hi:[0,1,1]
	v_pk_fma_f32 v[10:11], v[88:89], v[168:169], v[10:11] op_sel_hi:[0,1,1]
	v_pk_fma_f32 v[46:47], v[90:91], v[176:177], v[10:11] op_sel_hi:[0,1,1]
	v_pk_fma_f32 v[10:11], v[8:9], v[114:115], v[44:45] op_sel_hi:[0,1,1]
	v_pk_fma_f32 v[8:9], v[8:9], v[116:117], v[42:43] op_sel_hi:[0,1,1]
	v_pk_fma_f32 v[10:11], v[32:33], v[126:127], v[10:11] op_sel_hi:[0,1,1]
	v_pk_fma_f32 v[8:9], v[32:33], v[128:129], v[8:9] op_sel_hi:[0,1,1]
	v_pk_fma_f32 v[10:11], v[80:81], v[134:135], v[10:11] op_sel_hi:[0,1,1]
	v_pk_fma_f32 v[8:9], v[80:81], v[136:137], v[8:9] op_sel_hi:[0,1,1]
	v_pk_fma_f32 v[10:11], v[82:83], v[146:147], v[10:11] op_sel_hi:[0,1,1]
	v_pk_fma_f32 v[8:9], v[82:83], v[148:149], v[8:9] op_sel_hi:[0,1,1]
	v_pk_fma_f32 v[52:53], v[94:95], v[150:151], v[52:53] op_sel_hi:[0,1,1]
	v_pk_fma_f32 v[50:51], v[94:95], v[152:153], v[50:51] op_sel_hi:[0,1,1]
	v_pk_fma_f32 v[12:13], v[94:95], v[154:155], v[12:13] op_sel_hi:[0,1,1]
	v_pk_fma_f32 v[14:15], v[94:95], v[156:157], v[14:15] op_sel_hi:[0,1,1]
	v_pk_fma_f32 v[16:17], v[94:95], v[150:151], v[16:17] op_sel:[1,0,0]
	v_pk_fma_f32 v[18:19], v[94:95], v[152:153], v[18:19] op_sel:[1,0,0]
	v_pk_fma_f32 v[20:21], v[94:95], v[154:155], v[20:21] op_sel:[1,0,0]
	v_pk_fma_f32 v[10:11], v[84:85], v[154:155], v[10:11] op_sel_hi:[0,1,1]
	v_pk_fma_f32 v[8:9], v[84:85], v[156:157], v[8:9] op_sel_hi:[0,1,1]
	v_pk_fma_f32 v[52:53], v[98:99], v[158:159], v[52:53] op_sel_hi:[0,1,1]
	v_pk_fma_f32 v[50:51], v[98:99], v[160:161], v[50:51] op_sel_hi:[0,1,1]
	v_pk_fma_f32 v[12:13], v[98:99], v[162:163], v[12:13] op_sel_hi:[0,1,1]
	v_pk_fma_f32 v[14:15], v[98:99], v[164:165], v[14:15] op_sel_hi:[0,1,1]
	v_pk_fma_f32 v[16:17], v[98:99], v[158:159], v[16:17] op_sel:[1,0,0]
	v_pk_fma_f32 v[18:19], v[98:99], v[160:161], v[18:19] op_sel:[1,0,0]
	v_pk_fma_f32 v[20:21], v[98:99], v[162:163], v[20:21] op_sel:[1,0,0]
	v_pk_fma_f32 v[10:11], v[86:87], v[162:163], v[10:11] op_sel_hi:[0,1,1]
	v_pk_fma_f32 v[8:9], v[86:87], v[164:165], v[8:9] op_sel_hi:[0,1,1]
	v_pk_fma_f32 v[52:53], v[102:103], v[166:167], v[52:53] op_sel_hi:[0,1,1]
	v_pk_fma_f32 v[50:51], v[102:103], v[168:169], v[50:51] op_sel_hi:[0,1,1]
	v_pk_fma_f32 v[12:13], v[102:103], v[170:171], v[12:13] op_sel_hi:[0,1,1]
	v_pk_fma_f32 v[14:15], v[102:103], v[172:173], v[14:15] op_sel_hi:[0,1,1]
	v_pk_fma_f32 v[16:17], v[102:103], v[166:167], v[16:17] op_sel:[1,0,0]
	v_pk_fma_f32 v[18:19], v[102:103], v[168:169], v[18:19] op_sel:[1,0,0]
	v_pk_fma_f32 v[20:21], v[102:103], v[170:171], v[20:21] op_sel:[1,0,0]
	v_pk_fma_f32 v[10:11], v[88:89], v[170:171], v[10:11] op_sel_hi:[0,1,1]
	v_pk_fma_f32 v[8:9], v[88:89], v[172:173], v[8:9] op_sel_hi:[0,1,1]
	v_pk_fma_f32 v[52:53], v[106:107], v[174:175], v[52:53] op_sel_hi:[0,1,1]
	v_pk_fma_f32 v[50:51], v[106:107], v[176:177], v[50:51] op_sel_hi:[0,1,1]
	v_pk_fma_f32 v[12:13], v[106:107], v[178:179], v[12:13] op_sel_hi:[0,1,1]
	v_pk_fma_f32 v[14:15], v[106:107], v[180:181], v[14:15] op_sel_hi:[0,1,1]
	v_pk_fma_f32 v[16:17], v[106:107], v[174:175], v[16:17] op_sel:[1,0,0]
	v_pk_fma_f32 v[18:19], v[106:107], v[176:177], v[18:19] op_sel:[1,0,0]
	v_pk_fma_f32 v[20:21], v[106:107], v[178:179], v[20:21] op_sel:[1,0,0]
	v_pk_fma_f32 v[44:45], v[90:91], v[178:179], v[10:11] op_sel_hi:[0,1,1]
	v_pk_fma_f32 v[42:43], v[90:91], v[180:181], v[8:9] op_sel_hi:[0,1,1]
	s_cbranch_scc1 .LBB0_165
	v_mul_f32_e64 v8, v66, |v4|
	v_mul_f32_e32 v9, 0x3fb8aa3b, v8
	v_fma_f32 v10, v8, s84, -v9
	v_rndne_f32_e32 v11, v9
	v_fmac_f32_e32 v10, 0x32a5705f, v8
	v_sub_f32_e32 v9, v9, v11
	v_add_f32_e32 v9, v9, v10
	v_cvt_i32_f32_e32 v10, v11
	v_exp_f32_e32 v9, v9
	v_cmp_ngt_f32_e32 vcc, s85, v8
	v_ldexp_f32 v9, v9, v10
	v_mul_f32_e64 v10, v66, |v5|
	v_mul_f32_e32 v11, 0x3fb8aa3b, v10
	v_fma_f32 v32, v10, s84, -v11
	v_rndne_f32_e32 v41, v11
	v_fmac_f32_e32 v32, 0x32a5705f, v10
	v_sub_f32_e32 v11, v11, v41
	v_add_f32_e32 v11, v11, v32
	v_exp_f32_e32 v11, v11
	v_cvt_i32_f32_e32 v32, v41
	v_cndmask_b32_e32 v9, 0, v9, vcc
	v_cmp_nlt_f32_e32 vcc, s86, v8
	s_nop 1
	v_cndmask_b32_e32 v8, v78, v9, vcc
	v_ldexp_f32 v9, v11, v32
	v_mul_f32_e64 v11, v66, |v6|
	v_mul_f32_e32 v32, 0x3fb8aa3b, v11
	v_fma_f32 v41, v11, s84, -v32
	v_rndne_f32_e32 v54, v32
	v_fmac_f32_e32 v41, 0x32a5705f, v11
	v_sub_f32_e32 v32, v32, v54
	v_add_f32_e32 v32, v32, v41
	v_exp_f32_e32 v32, v32
	v_cvt_i32_f32_e32 v41, v54
	v_cmp_ngt_f32_e32 vcc, s85, v10
	s_nop 1
	v_cndmask_b32_e32 v9, 0, v9, vcc
	v_cmp_nlt_f32_e32 vcc, s86, v10
	v_ldexp_f32 v10, v32, v41
	v_mul_f32_e64 v32, v66, |v7|
	v_cndmask_b32_e32 v9, v78, v9, vcc
	v_mul_f32_e32 v41, 0x3fb8aa3b, v32
	v_pk_mul_f32 v[8:9], v[8:9], v[52:53]
	v_fma_f32 v52, v32, s84, -v41
	v_rndne_f32_e32 v53, v41
	v_fmac_f32_e32 v52, 0x32a5705f, v32
	v_sub_f32_e32 v41, v41, v53
	v_add_f32_e32 v41, v41, v52
	v_exp_f32_e32 v41, v41
	v_cvt_i32_f32_e32 v52, v53
	v_cmp_ngt_f32_e32 vcc, s85, v11
	s_nop 1
	v_cndmask_b32_e32 v10, 0, v10, vcc
	v_cmp_nlt_f32_e32 vcc, s86, v11
	v_ldexp_f32 v11, v41, v52
	v_mul_f32_e64 v41, v66, |v0|
	v_mul_f32_e32 v52, 0x3fb8aa3b, v41
	v_fma_f32 v53, v41, s84, -v52
	v_rndne_f32_e32 v54, v52
	v_fmac_f32_e32 v53, 0x32a5705f, v41
	v_sub_f32_e32 v52, v52, v54
	v_cndmask_b32_e32 v10, v78, v10, vcc
	v_cmp_ngt_f32_e32 vcc, s85, v32
	v_add_f32_e32 v52, v52, v53
	v_exp_f32_e32 v52, v52
	v_cndmask_b32_e32 v11, 0, v11, vcc
	v_cvt_i32_f32_e32 v53, v54
	v_cmp_nlt_f32_e32 vcc, s86, v32
	v_ldexp_f32 v32, v52, v53
	s_nop 0
	v_cndmask_b32_e32 v11, v78, v11, vcc
	v_pk_mul_f32 v[10:11], v[10:11], v[50:51]
	v_mul_f32_e64 v51, v66, |v1|
	v_mul_f32_e32 v50, 0x3fb8aa3b, v51
	v_fma_f32 v52, v51, s84, -v50
	v_rndne_f32_e32 v53, v50
	v_fmac_f32_e32 v52, 0x32a5705f, v51
	v_sub_f32_e32 v50, v50, v53
	v_add_f32_e32 v50, v50, v52
	v_exp_f32_e32 v52, v50
	v_cvt_i32_f32_e32 v53, v53
	v_cmp_ngt_f32_e32 vcc, s85, v41
	s_nop 1
	v_cndmask_b32_e32 v32, 0, v32, vcc
	v_cmp_nlt_f32_e32 vcc, s86, v41
	v_mul_f32_e64 v41, v66, |v2|
	s_nop 0
	v_cndmask_b32_e32 v50, v78, v32, vcc
	v_ldexp_f32 v32, v52, v53
	v_mul_f32_e32 v52, 0x3fb8aa3b, v41
	v_fma_f32 v53, v41, s84, -v52
	v_rndne_f32_e32 v54, v52
	v_fmac_f32_e32 v53, 0x32a5705f, v41
	v_sub_f32_e32 v52, v52, v54
	v_cmp_ngt_f32_e32 vcc, s85, v51
	v_add_f32_e32 v52, v52, v53
	v_exp_f32_e32 v52, v52
	v_cndmask_b32_e32 v32, 0, v32, vcc
	v_cvt_i32_f32_e32 v53, v54
	v_cmp_nlt_f32_e32 vcc, s86, v51
	s_nop 1
	v_cndmask_b32_e32 v51, v78, v32, vcc
	v_pk_mul_f32 v[12:13], v[50:51], v[12:13]
	v_mul_f32_e64 v51, v66, |v3|
	v_mul_f32_e32 v50, 0x3fb8aa3b, v51
	v_ldexp_f32 v32, v52, v53
	v_fma_f32 v52, v51, s84, -v50
	v_rndne_f32_e32 v53, v50
	v_fmac_f32_e32 v52, 0x32a5705f, v51
	v_sub_f32_e32 v50, v50, v53
	v_add_f32_e32 v50, v50, v52
	v_exp_f32_e32 v52, v50
	v_cvt_i32_f32_e32 v53, v53
	v_cmp_ngt_f32_e32 vcc, s85, v41
	s_nop 1
	v_cndmask_b32_e32 v32, 0, v32, vcc
	v_cmp_nlt_f32_e32 vcc, s86, v41
	s_nop 1
	v_cndmask_b32_e32 v50, v78, v32, vcc
	v_ldexp_f32 v32, v52, v53
	v_cmp_ngt_f32_e32 vcc, s85, v51
	s_nop 1
	v_cndmask_b32_e32 v32, 0, v32, vcc
	v_cmp_nlt_f32_e32 vcc, s86, v51
	s_nop 1
	v_cndmask_b32_e32 v51, v78, v32, vcc
	v_mul_f32_e64 v32, v67, |v4|
	v_mul_f32_e32 v41, 0x3fb8aa3b, v32
	v_fma_f32 v52, v32, s84, -v41
	v_rndne_f32_e32 v53, v41
	v_fmac_f32_e32 v52, 0x32a5705f, v32
	v_sub_f32_e32 v41, v41, v53
	v_add_f32_e32 v41, v41, v52
	v_exp_f32_e32 v41, v41
	v_cvt_i32_f32_e32 v52, v53
	v_pk_mul_f32 v[14:15], v[50:51], v[14:15]
	v_mul_f32_e64 v51, v67, |v5|
	v_mul_f32_e32 v50, 0x3fb8aa3b, v51
	v_ldexp_f32 v41, v41, v52
	v_fma_f32 v52, v51, s84, -v50
	v_rndne_f32_e32 v53, v50
	v_fmac_f32_e32 v52, 0x32a5705f, v51
	v_sub_f32_e32 v50, v50, v53
	v_add_f32_e32 v50, v50, v52
	v_exp_f32_e32 v52, v50
	v_cvt_i32_f32_e32 v53, v53
	v_cmp_ngt_f32_e32 vcc, s85, v32
	ds_write_b128 v74, v[8:11]
	ds_write_b128 v74, v[12:15] offset:16
	v_cndmask_b32_e32 v41, 0, v41, vcc
	v_cmp_nlt_f32_e32 vcc, s86, v32
	v_ldexp_f32 v32, v52, v53
	s_nop 0
	v_cndmask_b32_e32 v50, v78, v41, vcc
	v_mul_f32_e64 v41, v67, |v6|
	v_mul_f32_e32 v52, 0x3fb8aa3b, v41
	v_fma_f32 v53, v41, s84, -v52
	v_rndne_f32_e32 v54, v52
	v_fmac_f32_e32 v53, 0x32a5705f, v41
	v_sub_f32_e32 v52, v52, v54
	v_cmp_ngt_f32_e32 vcc, s85, v51
	v_add_f32_e32 v52, v52, v53
	v_exp_f32_e32 v52, v52
	v_cndmask_b32_e32 v32, 0, v32, vcc
	v_cvt_i32_f32_e32 v53, v54
	v_cmp_nlt_f32_e32 vcc, s86, v51
	s_nop 1
	v_cndmask_b32_e32 v51, v78, v32, vcc
	v_pk_mul_f32 v[16:17], v[50:51], v[16:17]
	v_mul_f32_e64 v51, v67, |v7|
	v_mul_f32_e32 v50, 0x3fb8aa3b, v51
	v_ldexp_f32 v32, v52, v53
	v_fma_f32 v52, v51, s84, -v50
	v_rndne_f32_e32 v53, v50
	v_fmac_f32_e32 v52, 0x32a5705f, v51
	v_sub_f32_e32 v50, v50, v53
	v_add_f32_e32 v50, v50, v52
	v_exp_f32_e32 v52, v50
	v_cvt_i32_f32_e32 v53, v53
	v_cmp_ngt_f32_e32 vcc, s85, v41
	v_add_f32_e64 v8, |v16|, |v8|
	s_nop 0
	v_cndmask_b32_e32 v32, 0, v32, vcc
	v_cmp_nlt_f32_e32 vcc, s86, v41
	v_mul_f32_e64 v41, v67, |v0|
	s_nop 0
	v_cndmask_b32_e32 v50, v78, v32, vcc
	v_ldexp_f32 v32, v52, v53
	v_mul_f32_e32 v52, 0x3fb8aa3b, v41
	v_fma_f32 v53, v41, s84, -v52
	v_rndne_f32_e32 v54, v52
	v_fmac_f32_e32 v53, 0x32a5705f, v41
	v_sub_f32_e32 v52, v52, v54
	v_cmp_ngt_f32_e32 vcc, s85, v51
	v_add_f32_e32 v52, v52, v53
	v_exp_f32_e32 v52, v52
	v_cndmask_b32_e32 v32, 0, v32, vcc
	v_cvt_i32_f32_e32 v53, v54
	v_cmp_nlt_f32_e32 vcc, s86, v51
	s_nop 1
	v_cndmask_b32_e32 v51, v78, v32, vcc
	v_pk_mul_f32 v[18:19], v[50:51], v[18:19]
	v_mul_f32_e64 v51, v67, |v1|
	v_mul_f32_e32 v50, 0x3fb8aa3b, v51
	v_ldexp_f32 v32, v52, v53
	v_fma_f32 v52, v51, s84, -v50
	v_rndne_f32_e32 v53, v50
	v_fmac_f32_e32 v52, 0x32a5705f, v51
	v_sub_f32_e32 v50, v50, v53
	v_add_f32_e32 v50, v50, v52
	v_exp_f32_e32 v52, v50
	v_cvt_i32_f32_e32 v53, v53
	v_cmp_ngt_f32_e32 vcc, s85, v41
	s_nop 1
	v_cndmask_b32_e32 v32, 0, v32, vcc
	v_cmp_nlt_f32_e32 vcc, s86, v41
	v_mul_f32_e64 v41, v67, |v2|
	s_nop 0
	v_cndmask_b32_e32 v50, v78, v32, vcc
	v_ldexp_f32 v32, v52, v53
	v_mul_f32_e32 v52, 0x3fb8aa3b, v41
	v_fma_f32 v53, v41, s84, -v52
	v_rndne_f32_e32 v54, v52
	v_fmac_f32_e32 v53, 0x32a5705f, v41
	v_sub_f32_e32 v52, v52, v54
	v_cmp_ngt_f32_e32 vcc, s85, v51
	v_add_f32_e32 v52, v52, v53
	v_exp_f32_e32 v52, v52
	v_cndmask_b32_e32 v32, 0, v32, vcc
	v_cvt_i32_f32_e32 v53, v54
	v_cmp_nlt_f32_e32 vcc, s86, v51
	s_nop 1
	v_cndmask_b32_e32 v51, v78, v32, vcc
	v_pk_mul_f32 v[20:21], v[50:51], v[20:21]
	v_mul_f32_e64 v51, v67, |v3|
	v_mul_f32_e32 v50, 0x3fb8aa3b, v51
	v_ldexp_f32 v32, v52, v53
	v_fma_f32 v52, v51, s84, -v50
	v_rndne_f32_e32 v53, v50
	v_fmac_f32_e32 v52, 0x32a5705f, v51
	v_sub_f32_e32 v50, v50, v53
	v_add_f32_e32 v50, v50, v52
	v_exp_f32_e32 v52, v50
	v_cvt_i32_f32_e32 v53, v53
	v_cmp_ngt_f32_e32 vcc, s85, v41
	s_nop 1
	v_cndmask_b32_e32 v32, 0, v32, vcc
	v_cmp_nlt_f32_e32 vcc, s86, v41
	s_nop 1
	v_cndmask_b32_e32 v50, v78, v32, vcc
	v_ldexp_f32 v32, v52, v53
	v_cmp_ngt_f32_e32 vcc, s85, v51
	s_nop 1
	v_cndmask_b32_e32 v32, 0, v32, vcc
	v_cmp_nlt_f32_e32 vcc, s86, v51
	s_nop 1
	v_cndmask_b32_e32 v51, v78, v32, vcc
	v_mul_f32_e64 v32, v68, |v4|
	v_mul_f32_e32 v41, 0x3fb8aa3b, v32
	v_fma_f32 v52, v32, s84, -v41
	v_rndne_f32_e32 v53, v41
	v_fmac_f32_e32 v52, 0x32a5705f, v32
	v_sub_f32_e32 v41, v41, v53
	v_add_f32_e32 v41, v41, v52
	v_exp_f32_e32 v41, v41
	v_cvt_i32_f32_e32 v52, v53
	v_pk_mul_f32 v[22:23], v[50:51], v[22:23]
	ds_write_b128 v75, v[16:19]
	ds_write_b128 v75, v[20:23] offset:16
	v_cmp_ngt_f32_e32 vcc, s85, v32
	v_ldexp_f32 v16, v41, v52
	v_mul_f32_e64 v41, v68, |v5|
	v_mul_f32_e32 v50, 0x3fb8aa3b, v41
	v_fma_f32 v51, v41, s84, -v50
	v_rndne_f32_e32 v52, v50
	v_fmac_f32_e32 v51, 0x32a5705f, v41
	v_sub_f32_e32 v50, v50, v52
	v_add_f32_e32 v50, v50, v51
	v_exp_f32_e32 v51, v50
	v_cvt_i32_f32_e32 v52, v52
	v_cndmask_b32_e32 v16, 0, v16, vcc
	v_cmp_nlt_f32_e32 vcc, s86, v32
	v_mul_f32_e64 v32, v68, |v6|
	v_mul_f32_e64 v4, v69, |v4|
	v_cndmask_b32_e32 v50, v78, v16, vcc
	v_ldexp_f32 v16, v51, v52
	v_mul_f32_e32 v51, 0x3fb8aa3b, v32
	v_fma_f32 v52, v32, s84, -v51
	v_rndne_f32_e32 v53, v51
	v_fmac_f32_e32 v52, 0x32a5705f, v32
	v_sub_f32_e32 v51, v51, v53
	v_add_f32_e32 v51, v51, v52
	v_cmp_ngt_f32_e32 vcc, s85, v41
	v_exp_f32_e32 v52, v51
	v_cvt_i32_f32_e32 v53, v53
	v_cndmask_b32_e32 v16, 0, v16, vcc
	v_cmp_nlt_f32_e32 vcc, s86, v41
	v_mul_f32_e64 v41, v68, |v7|
	v_mul_f32_e64 v5, v69, |v5|
	v_cndmask_b32_e32 v51, v78, v16, vcc
	v_pk_mul_f32 v[24:25], v[50:51], v[24:25]
	v_mul_f32_e32 v50, 0x3fb8aa3b, v41
	v_ldexp_f32 v16, v52, v53
	v_fma_f32 v51, v41, s84, -v50
	v_rndne_f32_e32 v52, v50
	v_fmac_f32_e32 v51, 0x32a5705f, v41
	v_sub_f32_e32 v50, v50, v52
	v_add_f32_e32 v50, v50, v51
	v_exp_f32_e32 v51, v50
	v_cvt_i32_f32_e32 v52, v52
	v_cmp_ngt_f32_e32 vcc, s85, v32
	v_add_f32_e64 v8, |v24|, v8
	v_mul_f32_e64 v6, v69, |v6|
	v_cndmask_b32_e32 v16, 0, v16, vcc
	v_cmp_nlt_f32_e32 vcc, s86, v32
	v_mul_f32_e64 v32, v68, |v0|
	v_mul_f32_e64 v7, v69, |v7|
	v_cndmask_b32_e32 v50, v78, v16, vcc
	v_ldexp_f32 v16, v51, v52
	v_mul_f32_e32 v51, 0x3fb8aa3b, v32
	v_fma_f32 v52, v32, s84, -v51
	v_rndne_f32_e32 v53, v51
	v_fmac_f32_e32 v52, 0x32a5705f, v32
	v_sub_f32_e32 v51, v51, v53
	v_add_f32_e32 v51, v51, v52
	v_cmp_ngt_f32_e32 vcc, s85, v41
	v_exp_f32_e32 v52, v51
	v_cvt_i32_f32_e32 v53, v53
	v_cndmask_b32_e32 v16, 0, v16, vcc
	v_cmp_nlt_f32_e32 vcc, s86, v41
	v_mul_f32_e64 v41, v68, |v1|
	v_mul_f32_e64 v0, v69, |v0|
	v_cndmask_b32_e32 v51, v78, v16, vcc
	v_pk_mul_f32 v[26:27], v[50:51], v[26:27]
	v_mul_f32_e32 v50, 0x3fb8aa3b, v41
	v_ldexp_f32 v16, v52, v53
	v_fma_f32 v51, v41, s84, -v50
	v_rndne_f32_e32 v52, v50
	v_fmac_f32_e32 v51, 0x32a5705f, v41
	v_sub_f32_e32 v50, v50, v52
	v_add_f32_e32 v50, v50, v51
	v_exp_f32_e32 v51, v50
	v_cvt_i32_f32_e32 v52, v52
	v_cmp_ngt_f32_e32 vcc, s85, v32
	v_mul_f32_e64 v1, v69, |v1|
	s_nop 0
	v_cndmask_b32_e32 v16, 0, v16, vcc
	v_cmp_nlt_f32_e32 vcc, s86, v32
	v_mul_f32_e64 v32, v68, |v2|
	v_mul_f32_e64 v2, v69, |v2|
	v_cndmask_b32_e32 v50, v78, v16, vcc
	v_ldexp_f32 v16, v51, v52
	v_mul_f32_e32 v51, 0x3fb8aa3b, v32
	v_fma_f32 v52, v32, s84, -v51
	v_rndne_f32_e32 v53, v51
	v_fmac_f32_e32 v52, 0x32a5705f, v32
	v_sub_f32_e32 v51, v51, v53
	v_add_f32_e32 v51, v51, v52
	v_cmp_ngt_f32_e32 vcc, s85, v41
	v_exp_f32_e32 v52, v51
	v_cvt_i32_f32_e32 v53, v53
	v_cndmask_b32_e32 v16, 0, v16, vcc
	v_cmp_nlt_f32_e32 vcc, s86, v41
	v_mul_f32_e64 v41, v68, |v3|
	v_mul_f32_e64 v3, v69, |v3|
	v_cndmask_b32_e32 v51, v78, v16, vcc
	v_pk_mul_f32 v[28:29], v[50:51], v[28:29]
	v_mul_f32_e32 v50, 0x3fb8aa3b, v41
	v_ldexp_f32 v16, v52, v53
	v_fma_f32 v51, v41, s84, -v50
	v_rndne_f32_e32 v52, v50
	v_fmac_f32_e32 v51, 0x32a5705f, v41
	v_sub_f32_e32 v50, v50, v52
	v_add_f32_e32 v50, v50, v51
	v_exp_f32_e32 v51, v50
	v_cvt_i32_f32_e32 v52, v52
	v_cmp_ngt_f32_e32 vcc, s85, v32
	s_nop 1
	v_cndmask_b32_e32 v16, 0, v16, vcc
	v_cmp_nlt_f32_e32 vcc, s86, v32
	s_nop 1
	v_cndmask_b32_e32 v50, v78, v16, vcc
	v_ldexp_f32 v16, v51, v52
	v_cmp_ngt_f32_e32 vcc, s85, v41
	s_nop 1
	v_cndmask_b32_e32 v16, 0, v16, vcc
	v_cmp_nlt_f32_e32 vcc, s86, v41
	s_nop 1
	v_cndmask_b32_e32 v51, v78, v16, vcc
	v_mul_f32_e32 v16, 0x3fb8aa3b, v4
	v_fma_f32 v32, v4, s84, -v16
	v_rndne_f32_e32 v41, v16
	v_fmac_f32_e32 v32, 0x32a5705f, v4
	v_sub_f32_e32 v16, v16, v41
	v_add_f32_e32 v16, v16, v32
	v_exp_f32_e32 v16, v16
	v_cvt_i32_f32_e32 v32, v41
	v_pk_mul_f32 v[30:31], v[50:51], v[30:31]
	ds_write_b128 v76, v[24:27]
	ds_write_b128 v76, v[28:31] offset:16
	v_mul_f32_e32 v24, 0x3fb8aa3b, v5
	v_ldexp_f32 v16, v16, v32
	v_fma_f32 v32, v5, s84, -v24
	v_rndne_f32_e32 v41, v24
	v_fmac_f32_e32 v32, 0x32a5705f, v5
	v_sub_f32_e32 v24, v24, v41
	v_add_f32_e32 v24, v24, v32
	v_exp_f32_e32 v24, v24
	v_cvt_i32_f32_e32 v32, v41
	v_cmp_ngt_f32_e32 vcc, s85, v4
	s_nop 1
	v_cndmask_b32_e32 v16, 0, v16, vcc
	v_cmp_nlt_f32_e32 vcc, s86, v4
	s_nop 1
	v_cndmask_b32_e32 v4, v78, v16, vcc
	v_ldexp_f32 v16, v24, v32
	v_mul_f32_e32 v24, 0x3fb8aa3b, v6
	v_fma_f32 v32, v6, s84, -v24
	v_rndne_f32_e32 v41, v24
	v_fmac_f32_e32 v32, 0x32a5705f, v6
	v_sub_f32_e32 v24, v24, v41
	v_add_f32_e32 v24, v24, v32
	v_exp_f32_e32 v24, v24
	v_cvt_i32_f32_e32 v32, v41
	v_cmp_ngt_f32_e32 vcc, s85, v5
	s_nop 1
	v_cndmask_b32_e32 v16, 0, v16, vcc
	v_cmp_nlt_f32_e32 vcc, s86, v5
	s_nop 1
	v_cndmask_b32_e32 v5, v78, v16, vcc
	v_ldexp_f32 v16, v24, v32
	v_mul_f32_e32 v24, 0x3fb8aa3b, v7
	v_fma_f32 v32, v7, s84, -v24
	v_rndne_f32_e32 v41, v24
	v_fmac_f32_e32 v32, 0x32a5705f, v7
	v_sub_f32_e32 v24, v24, v41
	v_add_f32_e32 v24, v24, v32
	v_exp_f32_e32 v24, v24
	v_cvt_i32_f32_e32 v32, v41
	v_cmp_ngt_f32_e32 vcc, s85, v6
	v_pk_mul_f32 v[4:5], v[4:5], v[48:49]
	s_nop 0
	v_cndmask_b32_e32 v16, 0, v16, vcc
	v_cmp_nlt_f32_e32 vcc, s86, v6
	v_add_f32_e64 v8, |v4|, v8
	s_nop 0
	v_cndmask_b32_e32 v6, v78, v16, vcc
	v_ldexp_f32 v16, v24, v32
	v_mul_f32_e32 v24, 0x3fb8aa3b, v0
	v_fma_f32 v32, v0, s84, -v24
	v_rndne_f32_e32 v41, v24
	v_fmac_f32_e32 v32, 0x32a5705f, v0
	v_sub_f32_e32 v24, v24, v41
	v_add_f32_e32 v24, v24, v32
	v_exp_f32_e32 v24, v24
	v_cvt_i32_f32_e32 v32, v41
	v_cmp_ngt_f32_e32 vcc, s85, v7
	s_nop 1
	v_cndmask_b32_e32 v16, 0, v16, vcc
	v_cmp_nlt_f32_e32 vcc, s86, v7
	s_nop 1
	v_cndmask_b32_e32 v7, v78, v16, vcc
	v_ldexp_f32 v16, v24, v32
	v_mul_f32_e32 v24, 0x3fb8aa3b, v1
	v_fma_f32 v32, v1, s84, -v24
	v_rndne_f32_e32 v41, v24
	v_fmac_f32_e32 v32, 0x32a5705f, v1
	v_sub_f32_e32 v24, v24, v41
	v_add_f32_e32 v24, v24, v32
	v_exp_f32_e32 v24, v24
	v_cvt_i32_f32_e32 v32, v41
	v_cmp_ngt_f32_e32 vcc, s85, v0
	ds_bpermute_b32 v41, v56, v8
	v_pk_mul_f32 v[6:7], v[6:7], v[46:47]
	v_cndmask_b32_e32 v16, 0, v16, vcc
	v_cmp_nlt_f32_e32 vcc, s86, v0
	s_waitcnt lgkmcnt(0)
	v_add_f32_e32 v8, v8, v41
	v_cndmask_b32_e32 v0, v78, v16, vcc
	v_ldexp_f32 v16, v24, v32
	v_cmp_ngt_f32_e32 vcc, s85, v1
	s_nop 1
	v_cndmask_b32_e32 v16, 0, v16, vcc
	v_cmp_nlt_f32_e32 vcc, s86, v1
	s_nop 1
	v_cndmask_b32_e32 v1, v78, v16, vcc
	v_mul_f32_e32 v16, 0x3fb8aa3b, v2
	v_fma_f32 v24, v2, s84, -v16
	v_rndne_f32_e32 v32, v16
	v_fmac_f32_e32 v24, 0x32a5705f, v2
	v_sub_f32_e32 v16, v16, v32
	v_add_f32_e32 v16, v16, v24
	v_cvt_i32_f32_e32 v24, v32
	ds_bpermute_b32 v32, v57, v8
	v_exp_f32_e32 v16, v16
	v_pk_mul_f32 v[0:1], v[0:1], v[44:45]
	v_cmp_ngt_f32_e32 vcc, s85, v2
	s_waitcnt lgkmcnt(0)
	v_add_f32_e32 v8, v8, v32
	v_ldexp_f32 v16, v16, v24
	ds_bpermute_b32 v24, v58, v8
	v_mul_f32_e32 v32, 0x3fb8aa3b, v3
	v_fma_f32 v41, v3, s84, -v32
	v_rndne_f32_e32 v44, v32
	v_fmac_f32_e32 v41, 0x32a5705f, v3
	s_waitcnt lgkmcnt(0)
	v_add_f32_e32 v8, v8, v24
	ds_bpermute_b32 v24, v59, v8
	v_sub_f32_e32 v32, v32, v44
	v_add_f32_e32 v32, v32, v41
	v_exp_f32_e32 v32, v32
	v_cvt_i32_f32_e32 v41, v44
	s_waitcnt lgkmcnt(0)
	v_add_f32_e32 v8, v8, v24
	ds_bpermute_b32 v24, v60, v8
	v_cndmask_b32_e32 v16, 0, v16, vcc
	v_cmp_nlt_f32_e32 vcc, s86, v2
	s_waitcnt lgkmcnt(0)
	v_add_f32_e32 v8, v8, v24
	v_cndmask_b32_e32 v2, v78, v16, vcc
	v_ldexp_f32 v16, v32, v41
	v_cmp_ngt_f32_e32 vcc, s85, v3
	s_nop 1
	v_cndmask_b32_e32 v32, 0, v16, vcc
	ds_bpermute_b32 v16, v61, v8
	v_cmp_nlt_f32_e32 vcc, s86, v3
	s_nop 1
	v_cndmask_b32_e32 v3, v78, v32, vcc
	v_pk_mul_f32 v[2:3], v[2:3], v[42:43]
	ds_write_b128 v77, v[4:7]
	ds_write_b128 v77, v[0:3] offset:16
	s_and_saveexec_b64 s[10:11], s[6:7]
	s_cbranch_execz .LBB0_168
	s_waitcnt lgkmcnt(2)
	v_add_f32_e32 v4, v8, v16
	v_add_u32_e32 v8, 0, v62
	v_add_u32_e32 v8, 0x10800, v8
	ds_write_b32 v8, v4
